# halo fix-up loop: second wait counts past the G store (vmcnt(1))
# baseline (speedup 1.0000x reference)
.LBB0_289:
	v_add_co_u32_e32 v42, vcc, 0x3000, v40
	s_mov_b32 s13, 0xc000
	s_nop 0
	v_addc_co_u32_e32 v43, vcc, 0, v41, vcc
	v_add_co_u32_e32 v44, vcc, 0x9000, v40
	s_mov_b32 s4, 0x12000
	s_nop 0
	v_addc_co_u32_e32 v45, vcc, 0, v41, vcc
	global_load_dwordx4 v[160:163], v[42:43], off
	global_load_dwordx4 v[164:167], v[44:45], off
	v_add_co_u32_e32 v44, vcc, s13, v40
	v_lshl_add_u64 v[42:43], s[34:35], 0, v[38:39]
	s_nop 0
	v_addc_co_u32_e32 v45, vcc, 0, v41, vcc
	v_add_co_u32_e32 v46, vcc, s4, v40
	s_movk_i32 s5, 0x6000
	s_nop 0
	v_addc_co_u32_e32 v47, vcc, 0, v41, vcc
	global_load_dwordx4 v[114:117], v[44:45], off
	global_load_dwordx4 v[102:105], v[42:43], off
	v_add_co_u32_e32 v44, vcc, s5, v42
	s_mov_b32 s59, 0xf000
	s_nop 0
	v_addc_co_u32_e32 v45, vcc, 0, v43, vcc
	global_load_dwordx4 v[110:113], v[46:47], off
	global_load_dwordx4 v[106:109], v[44:45], off
	v_add_co_u32_e32 v44, vcc, s59, v40
	s_mov_b32 s60, 0x15000
	s_nop 0
	v_addc_co_u32_e32 v45, vcc, 0, v41, vcc
	v_add_co_u32_e32 v40, vcc, s60, v40
	s_movk_i32 s57, 0x3000
	s_nop 0
	v_addc_co_u32_e32 v41, vcc, 0, v41, vcc
	global_load_dwordx4 v[126:129], v[44:45], off
	global_load_dwordx4 v[118:121], v[40:41], off
	v_add_co_u32_e32 v40, vcc, s57, v42
	s_mov_b32 s58, 0x9000
	s_nop 0
	v_addc_co_u32_e32 v41, vcc, 0, v43, vcc
	v_add_co_u32_e32 v44, vcc, s58, v42
	s_waitcnt vmcnt(0) lgkmcnt(0)
	v_pk_fma_f32 v[142:143], v[26:27], v[142:143], v[30:31]
	v_addc_co_u32_e32 v45, vcc, 0, v43, vcc
	global_load_dwordx4 v[130:133], v[40:41], off
	global_load_dwordx4 v[122:125], v[44:45], off
	v_pk_fma_f32 v[142:143], v[22:23], v[138:139], v[142:143]
	v_lshl_add_u64 v[158:159], v[2:3], 1, s[10:11]
	v_pk_fma_f32 v[142:143], v[18:19], v[154:155], v[142:143]
	v_pk_fma_f32 v[144:145], v[28:29], v[144:145], v[32:33]
	v_mul_f32_e32 v3, v142, v142
	v_fmamk_f32 v3, v3, 0xbdd2d3e2, v220
	v_mul_f32_e32 v5, v143, v143
	v_mul_f32_e32 v3, v142, v3
	v_fmamk_f32 v5, v5, 0xbdd2d3e2, v220
	v_exp_f32_e32 v3, v3
	v_mul_f32_e32 v5, v143, v5
	v_exp_f32_e32 v5, v5
	v_add_co_u32_e32 v44, vcc, s13, v42
	v_pk_fma_f32 v[144:145], v[24:25], v[140:141], v[144:145]
	v_pk_fma_f32 v[138:139], v[26:27], v[138:139], v[30:31]
	v_addc_co_u32_e32 v45, vcc, 0, v43, vcc
	v_pk_fma_f32 v[144:145], v[20:21], v[156:157], v[144:145]
	v_pk_fma_f32 v[138:139], v[22:23], v[154:155], v[138:139]
	v_add_f32_e32 v3, 1.0, v3
	v_add_co_u32_e32 v46, vcc, s4, v42
	v_pk_fma_f32 v[138:139], v[18:19], v[150:151], v[138:139]
	v_rcp_f32_e32 v150, v3
	v_add_f32_e32 v3, 1.0, v5
	v_mul_f32_e32 v5, v144, v144
	v_lshl_add_u64 v[40:41], s[24:25], 0, v[38:39]
	v_addc_co_u32_e32 v47, vcc, 0, v43, vcc
	v_fmamk_f32 v5, v5, 0xbdd2d3e2, v220
	v_mul_f32_e32 v151, v145, v145
	global_load_dwordx4 v[98:101], v[44:45], off
	global_load_dwordx4 v[78:81], v[40:41], off
	v_add_co_u32_e32 v44, vcc, s5, v40
	v_pk_fma_f32 v[140:141], v[28:29], v[140:141], v[32:33]
	v_mul_f32_e32 v5, v144, v5
	v_fmamk_f32 v151, v151, 0xbdd2d3e2, v220
	v_addc_co_u32_e32 v45, vcc, 0, v41, vcc
	v_pk_fma_f32 v[140:141], v[24:25], v[156:157], v[140:141]
	v_exp_f32_e32 v5, v5
	v_mul_f32_e32 v151, v145, v151
	global_load_dwordx4 v[94:97], v[46:47], off
	global_load_dwordx4 v[82:85], v[44:45], off
	v_add_co_u32_e32 v44, vcc, s59, v42
	v_pk_fma_f32 v[140:141], v[20:21], v[152:153], v[140:141]
	v_exp_f32_e32 v153, v151
	v_addc_co_u32_e32 v45, vcc, 0, v43, vcc
	v_add_co_u32_e32 v42, vcc, s60, v42
	v_rcp_f32_e32 v152, v3
	s_nop 0
	v_addc_co_u32_e32 v43, vcc, 0, v43, vcc
	v_add_f32_e32 v3, 1.0, v5
	global_load_dwordx4 v[90:93], v[44:45], off
	global_load_dwordx4 v[74:77], v[42:43], off
	v_add_co_u32_e32 v42, vcc, s57, v40
	v_rcp_f32_e32 v151, v3
	v_add_f32_e32 v3, 1.0, v153
	v_addc_co_u32_e32 v43, vcc, 0, v41, vcc
	v_rcp_f32_e32 v153, v3
	v_add_co_u32_e32 v44, vcc, s58, v40
	v_pk_fma_f32 v[136:137], v[12:13], v[136:137], v[36:37]
	v_pk_fma_f32 v[134:135], v[10:11], v[134:135], v[34:35]
	v_addc_co_u32_e32 v45, vcc, 0, v41, vcc
	v_pk_fma_f32 v[136:137], v[16:17], v[148:149], v[136:137]
	v_pk_fma_f32 v[134:135], v[14:15], v[146:147], v[134:135]
	global_load_dwordx4 v[86:89], v[42:43], off
	global_load_dwordx4 v[70:73], v[44:45], off
	v_add_co_u32_e32 v42, vcc, s13, v40
	v_pk_fma_f32 v[136:137], v[8:9], v[162:163], v[136:137]
	v_pk_fma_f32 v[134:135], v[6:7], v[160:161], v[134:135]
	v_mov_b32_e32 v154, v142
	v_mov_b32_e32 v155, v144
	v_mov_b32_e32 v144, v143
	v_addc_co_u32_e32 v43, vcc, 0, v41, vcc
	v_pk_mul_f32 v[150:151], v[154:155], v[150:151]
	v_mov_b32_e32 v155, v136
	v_pk_mul_f32 v[142:143], v[144:145], v[152:153]
	v_mov_b32_e32 v136, v135
	v_add_co_u32_e32 v44, vcc, s4, v40
	v_mov_b32_e32 v154, v134
	v_pk_mul_f32 v[134:135], v[142:143], v[136:137]
	v_lshl_add_u64 v[38:39], s[36:37], 0, v[38:39]
	v_addc_co_u32_e32 v45, vcc, 0, v41, vcc
	v_pk_mul_f32 v[150:151], v[150:151], v[154:155]
	v_and_b32_sdwa v136, v135, v218 dst_sel:DWORD dst_unused:UNUSED_PAD src0_sel:WORD_1 src1_sel:DWORD
	global_load_dwordx4 v[62:65], v[42:43], off
	global_load_dwordx4 v[46:49], v[38:39], off
	v_add_co_u32_e32 v42, vcc, s5, v38
	v_and_b32_sdwa v3, v151, v218 dst_sel:DWORD dst_unused:UNUSED_PAD src0_sel:WORD_1 src1_sel:DWORD
	v_and_b32_sdwa v137, v134, v218 dst_sel:DWORD dst_unused:UNUSED_PAD src0_sel:WORD_1 src1_sel:DWORD
	v_add3_u32 v135, v135, v136, s91
	v_addc_co_u32_e32 v43, vcc, 0, v39, vcc
	v_and_b32_sdwa v5, v150, v218 dst_sel:DWORD dst_unused:UNUSED_PAD src0_sel:WORD_1 src1_sel:DWORD
	v_add3_u32 v3, v151, v3, s91
	v_add3_u32 v134, v134, v137, s91
	v_and_b32_e32 v135, 0xffff0000, v135
	global_load_dwordx4 v[54:57], v[44:45], off
	global_load_dwordx4 v[50:53], v[42:43], off
	v_add_co_u32_e32 v42, vcc, s60, v40
	v_add3_u32 v5, v150, v5, s91
	v_and_b32_e32 v134, 0xffff0000, v134
	v_or_b32_sdwa v135, v135, v3 dst_sel:DWORD dst_unused:UNUSED_PAD src0_sel:DWORD src1_sel:WORD_1
	v_mul_f32_e32 v3, v138, v138
	v_addc_co_u32_e32 v43, vcc, 0, v41, vcc
	v_or_b32_sdwa v134, v134, v5 dst_sel:DWORD dst_unused:UNUSED_PAD src0_sel:DWORD src1_sel:WORD_1
	v_fmamk_f32 v3, v3, 0xbdd2d3e2, v220
	v_mul_f32_e32 v5, v139, v139
	v_add_co_u32_e32 v40, vcc, s59, v40
	v_mul_f32_e32 v3, v138, v3
	v_fmamk_f32 v5, v5, 0xbdd2d3e2, v220
	v_addc_co_u32_e32 v41, vcc, 0, v41, vcc
	v_exp_f32_e32 v3, v3
	v_mul_f32_e32 v5, v139, v5
	global_load_dwordx4 v[42:45], v[42:43], off
	s_nop 0
	global_load_dwordx4 v[66:69], v[40:41], off
	v_add_co_u32_e32 v40, vcc, s57, v38
	v_exp_f32_e32 v5, v5
	s_nop 0
	v_addc_co_u32_e32 v41, vcc, 0, v39, vcc
	v_add_co_u32_e32 v38, vcc, s58, v38
	v_lshl_add_u64 v[136:137], v[158:159], 0, s[38:39]
	s_nop 0
	v_addc_co_u32_e32 v39, vcc, 0, v39, vcc
	v_add_f32_e32 v3, 1.0, v3
	global_load_dwordx4 v[58:61], v[40:41], off
	s_nop 0
	global_load_dwordx4 v[38:41], v[38:39], off
	v_pk_fma_f32 v[148:149], v[12:13], v[148:149], v[36:37]
	global_store_dwordx2 v[136:137], v[134:135], off
	v_rcp_f32_e32 v134, v3
	v_add_f32_e32 v3, 1.0, v5
	v_mul_f32_e32 v5, v140, v140
	v_fmamk_f32 v5, v5, 0xbdd2d3e2, v220
	v_mul_f32_e32 v135, v141, v141
	v_mul_f32_e32 v5, v140, v5
	v_fmamk_f32 v135, v135, 0xbdd2d3e2, v220
	v_exp_f32_e32 v5, v5
	v_mul_f32_e32 v135, v141, v135
	v_exp_f32_e32 v137, v135
	v_rcp_f32_e32 v136, v3
	v_add_f32_e32 v3, 1.0, v5
	v_rcp_f32_e32 v135, v3
	v_add_f32_e32 v3, 1.0, v137
	v_pk_fma_f32 v[146:147], v[10:11], v[146:147], v[34:35]
	v_rcp_f32_e32 v137, v3
	v_pk_fma_f32 v[148:149], v[16:17], v[162:163], v[148:149]
	v_pk_fma_f32 v[146:147], v[14:15], v[160:161], v[146:147]
	v_pk_fma_f32 v[148:149], v[8:9], v[166:167], v[148:149]
	v_pk_fma_f32 v[146:147], v[6:7], v[164:165], v[146:147]
	v_mov_b32_e32 v142, v138
	v_mov_b32_e32 v143, v140
	v_pk_mul_f32 v[134:135], v[142:143], v[134:135]
	v_mov_b32_e32 v142, v146
	v_mov_b32_e32 v143, v148
	v_mov_b32_e32 v140, v139
	v_pk_mul_f32 v[134:135], v[134:135], v[142:143]
	v_pk_mul_f32 v[136:137], v[140:141], v[136:137]
	v_mov_b32_e32 v148, v147
	v_pk_mul_f32 v[136:137], v[136:137], v[148:149]
	v_and_b32_sdwa v5, v134, v218 dst_sel:DWORD dst_unused:UNUSED_PAD src0_sel:WORD_1 src1_sel:DWORD
	v_and_b32_sdwa v3, v135, v218 dst_sel:DWORD dst_unused:UNUSED_PAD src0_sel:WORD_1 src1_sel:DWORD
	v_add3_u32 v5, v134, v5, s91
	v_and_b32_sdwa v134, v137, v218 dst_sel:DWORD dst_unused:UNUSED_PAD src0_sel:WORD_1 src1_sel:DWORD
	v_pk_fma_f32 v[114:115], v[26:27], v[114:115], v[30:31]
	v_add3_u32 v3, v135, v3, s91
	v_and_b32_sdwa v135, v136, v218 dst_sel:DWORD dst_unused:UNUSED_PAD src0_sel:WORD_1 src1_sel:DWORD
	v_add3_u32 v134, v137, v134, s91
	v_pk_fma_f32 v[114:115], v[22:23], v[110:111], v[114:115]
	v_add3_u32 v135, v136, v135, s91
	v_and_b32_e32 v134, 0xffff0000, v134
	v_pk_fma_f32 v[114:115], v[18:19], v[102:103], v[114:115]
	v_and_b32_e32 v136, 0xffff0000, v135
	v_or_b32_sdwa v135, v134, v3 dst_sel:DWORD dst_unused:UNUSED_PAD src0_sel:DWORD src1_sel:WORD_1
	v_mul_f32_e32 v3, v114, v114
	v_or_b32_sdwa v134, v136, v5 dst_sel:DWORD dst_unused:UNUSED_PAD src0_sel:DWORD src1_sel:WORD_1
	v_fmamk_f32 v3, v3, 0xbdd2d3e2, v220
	v_mul_f32_e32 v5, v115, v115
	v_mul_f32_e32 v3, v114, v3
	v_fmamk_f32 v5, v5, 0xbdd2d3e2, v220
	v_exp_f32_e32 v3, v3
	v_mul_f32_e32 v5, v115, v5
	v_pk_fma_f32 v[116:117], v[28:29], v[116:117], v[32:33]
	v_exp_f32_e32 v5, v5
	v_pk_fma_f32 v[116:117], v[24:25], v[112:113], v[116:117]
	v_pk_fma_f32 v[112:113], v[28:29], v[112:113], v[32:33]
	v_pk_fma_f32 v[116:117], v[20:21], v[104:105], v[116:117]
	v_pk_fma_f32 v[104:105], v[24:25], v[104:105], v[112:113]
	v_add_f32_e32 v3, 1.0, v3
	v_pk_fma_f32 v[104:105], v[20:21], v[108:109], v[104:105]
	v_pk_fma_f32 v[108:109], v[10:11], v[126:127], v[34:35]
	v_pk_fma_f32 v[112:113], v[10:11], v[118:119], v[34:35]
	v_pk_fma_f32 v[108:109], v[14:15], v[118:119], v[108:109]
	v_rcp_f32_e32 v118, v3
	v_add_f32_e32 v3, 1.0, v5
	v_mul_f32_e32 v5, v116, v116
	v_pk_fma_f32 v[110:111], v[26:27], v[110:111], v[30:31]
	v_fmamk_f32 v5, v5, 0xbdd2d3e2, v220
	v_mul_f32_e32 v119, v117, v117
	v_pk_fma_f32 v[102:103], v[22:23], v[102:103], v[110:111]
	v_mul_f32_e32 v5, v116, v5
	v_fmamk_f32 v119, v119, 0xbdd2d3e2, v220
	v_pk_fma_f32 v[102:103], v[18:19], v[106:107], v[102:103]
	v_pk_fma_f32 v[106:107], v[12:13], v[128:129], v[36:37]
	v_exp_f32_e32 v5, v5
	v_mul_f32_e32 v119, v117, v119
	v_pk_fma_f32 v[106:107], v[16:17], v[120:121], v[106:107]
	v_pk_fma_f32 v[110:111], v[12:13], v[120:121], v[36:37]
	v_exp_f32_e32 v121, v119
	v_rcp_f32_e32 v120, v3
	v_add_f32_e32 v3, 1.0, v5
	v_rcp_f32_e32 v119, v3
	v_add_f32_e32 v3, 1.0, v121
	v_rcp_f32_e32 v121, v3
	s_waitcnt vmcnt(1) lgkmcnt(0)
	v_pk_fma_f32 v[112:113], v[14:15], v[130:131], v[112:113]
	v_pk_fma_f32 v[106:107], v[8:9], v[132:133], v[106:107]
	v_pk_fma_f32 v[108:109], v[6:7], v[130:131], v[108:109]
	v_pk_fma_f32 v[112:113], v[6:7], v[122:123], v[112:113]
	v_mov_b32_e32 v122, v114
	v_mov_b32_e32 v123, v116
	v_mov_b32_e32 v116, v115
	v_pk_mul_f32 v[118:119], v[122:123], v[118:119]
	v_mov_b32_e32 v123, v106
	v_pk_mul_f32 v[114:115], v[116:117], v[120:121]
	v_mov_b32_e32 v106, v109
	v_mov_b32_e32 v122, v108
	v_pk_mul_f32 v[106:107], v[106:107], v[114:115]
	v_pk_mul_f32 v[118:119], v[122:123], v[118:119]
	v_and_b32_sdwa v108, v107, v218 dst_sel:DWORD dst_unused:UNUSED_PAD src0_sel:WORD_1 src1_sel:DWORD
	v_and_b32_sdwa v3, v119, v218 dst_sel:DWORD dst_unused:UNUSED_PAD src0_sel:WORD_1 src1_sel:DWORD
	v_and_b32_sdwa v109, v106, v218 dst_sel:DWORD dst_unused:UNUSED_PAD src0_sel:WORD_1 src1_sel:DWORD
	v_add3_u32 v107, v107, v108, s91
	v_and_b32_sdwa v5, v118, v218 dst_sel:DWORD dst_unused:UNUSED_PAD src0_sel:WORD_1 src1_sel:DWORD
	v_add3_u32 v3, v119, v3, s91
	v_add3_u32 v106, v106, v109, s91
	v_and_b32_e32 v107, 0xffff0000, v107
	v_add3_u32 v5, v118, v5, s91
	v_and_b32_e32 v106, 0xffff0000, v106
	v_or_b32_sdwa v107, v107, v3 dst_sel:DWORD dst_unused:UNUSED_PAD src0_sel:DWORD src1_sel:WORD_1
	v_mul_f32_e32 v3, v102, v102
	v_or_b32_sdwa v106, v106, v5 dst_sel:DWORD dst_unused:UNUSED_PAD src0_sel:DWORD src1_sel:WORD_1
	v_fmamk_f32 v3, v3, 0xbdd2d3e2, v220
	v_mul_f32_e32 v5, v103, v103
	v_mul_f32_e32 v3, v102, v3
	v_fmamk_f32 v5, v5, 0xbdd2d3e2, v220
	v_exp_f32_e32 v3, v3
	v_mul_f32_e32 v5, v103, v5
	v_exp_f32_e32 v5, v5
	v_lshl_add_u64 v[108:109], v[158:159], 0, s[42:43]
	v_add_f32_e32 v3, 1.0, v3
	global_store_dwordx2 v[108:109], v[106:107], off
	v_rcp_f32_e32 v106, v3
	v_add_f32_e32 v3, 1.0, v5
	v_mul_f32_e32 v5, v104, v104
	v_fmamk_f32 v5, v5, 0xbdd2d3e2, v220
	v_mul_f32_e32 v107, v105, v105
	v_mul_f32_e32 v5, v104, v5
	v_fmamk_f32 v107, v107, 0xbdd2d3e2, v220
	v_exp_f32_e32 v5, v5
	v_mul_f32_e32 v107, v105, v107
	v_exp_f32_e32 v109, v107
	v_rcp_f32_e32 v108, v3
	v_add_f32_e32 v3, 1.0, v5
	v_rcp_f32_e32 v107, v3
	v_add_f32_e32 v3, 1.0, v109
	v_rcp_f32_e32 v109, v3
	v_pk_fma_f32 v[110:111], v[16:17], v[132:133], v[110:111]
	v_mov_b32_e32 v114, v102
	v_pk_fma_f32 v[110:111], v[8:9], v[124:125], v[110:111]
	v_mov_b32_e32 v115, v104
	v_mov_b32_e32 v104, v103
	v_pk_mul_f32 v[106:107], v[114:115], v[106:107]
	v_mov_b32_e32 v115, v110
	v_pk_mul_f32 v[102:103], v[104:105], v[108:109]
	v_mov_b32_e32 v110, v113
	v_mov_b32_e32 v114, v112
	v_pk_mul_f32 v[102:103], v[110:111], v[102:103]
	v_pk_mul_f32 v[106:107], v[114:115], v[106:107]
	v_and_b32_sdwa v104, v103, v218 dst_sel:DWORD dst_unused:UNUSED_PAD src0_sel:WORD_1 src1_sel:DWORD
	v_pk_fma_f32 v[98:99], v[26:27], v[98:99], v[30:31]
	v_and_b32_sdwa v3, v107, v218 dst_sel:DWORD dst_unused:UNUSED_PAD src0_sel:WORD_1 src1_sel:DWORD
	v_and_b32_sdwa v105, v102, v218 dst_sel:DWORD dst_unused:UNUSED_PAD src0_sel:WORD_1 src1_sel:DWORD
	v_add3_u32 v103, v103, v104, s91
	v_pk_fma_f32 v[98:99], v[22:23], v[94:95], v[98:99]
	v_and_b32_sdwa v5, v106, v218 dst_sel:DWORD dst_unused:UNUSED_PAD src0_sel:WORD_1 src1_sel:DWORD
	v_add3_u32 v3, v107, v3, s91
	v_add3_u32 v102, v102, v105, s91
	v_and_b32_e32 v103, 0xffff0000, v103
	v_pk_fma_f32 v[98:99], v[18:19], v[78:79], v[98:99]
	v_add3_u32 v5, v106, v5, s91
	v_and_b32_e32 v102, 0xffff0000, v102
	v_or_b32_sdwa v103, v103, v3 dst_sel:DWORD dst_unused:UNUSED_PAD src0_sel:DWORD src1_sel:WORD_1
	v_mul_f32_e32 v3, v98, v98
	v_or_b32_sdwa v102, v102, v5 dst_sel:DWORD dst_unused:UNUSED_PAD src0_sel:DWORD src1_sel:WORD_1
	v_fmamk_f32 v3, v3, 0xbdd2d3e2, v220
	v_mul_f32_e32 v5, v99, v99
	v_pk_fma_f32 v[100:101], v[28:29], v[100:101], v[32:33]
	v_mul_f32_e32 v3, v98, v3
	v_fmamk_f32 v5, v5, 0xbdd2d3e2, v220
	v_pk_fma_f32 v[100:101], v[24:25], v[96:97], v[100:101]
	v_pk_fma_f32 v[96:97], v[28:29], v[96:97], v[32:33]
	v_exp_f32_e32 v3, v3
	v_mul_f32_e32 v5, v99, v5
	v_pk_fma_f32 v[100:101], v[20:21], v[80:81], v[100:101]
	v_pk_fma_f32 v[80:81], v[24:25], v[80:81], v[96:97]
	v_exp_f32_e32 v5, v5
	v_pk_fma_f32 v[80:81], v[20:21], v[84:85], v[80:81]
	v_pk_fma_f32 v[84:85], v[10:11], v[90:91], v[34:35]
	v_pk_fma_f32 v[94:95], v[26:27], v[94:95], v[30:31]
	v_pk_fma_f32 v[84:85], v[14:15], v[74:75], v[84:85]
	v_pk_fma_f32 v[74:75], v[10:11], v[74:75], v[34:35]
	v_add_f32_e32 v3, 1.0, v3
	v_pk_fma_f32 v[74:75], v[14:15], v[86:87], v[74:75]
	v_pk_fma_f32 v[78:79], v[22:23], v[78:79], v[94:95]
	v_pk_fma_f32 v[70:71], v[6:7], v[70:71], v[74:75]
	v_rcp_f32_e32 v74, v3
	v_add_f32_e32 v3, 1.0, v5
	v_mul_f32_e32 v5, v100, v100
	v_pk_fma_f32 v[78:79], v[18:19], v[82:83], v[78:79]
	v_pk_fma_f32 v[82:83], v[12:13], v[92:93], v[36:37]
	v_fmamk_f32 v5, v5, 0xbdd2d3e2, v220
	v_mul_f32_e32 v75, v101, v101
	v_pk_fma_f32 v[82:83], v[16:17], v[76:77], v[82:83]
	v_pk_fma_f32 v[76:77], v[12:13], v[76:77], v[36:37]
	v_mul_f32_e32 v5, v100, v5
	v_fmamk_f32 v75, v75, 0xbdd2d3e2, v220
	v_pk_fma_f32 v[76:77], v[16:17], v[88:89], v[76:77]
	v_exp_f32_e32 v5, v5
	v_mul_f32_e32 v75, v101, v75
	v_pk_fma_f32 v[72:73], v[8:9], v[72:73], v[76:77]
	v_exp_f32_e32 v77, v75
	v_rcp_f32_e32 v76, v3
	v_add_f32_e32 v3, 1.0, v5
	v_rcp_f32_e32 v75, v3
	v_add_f32_e32 v3, 1.0, v77
	v_rcp_f32_e32 v77, v3
	v_pk_fma_f32 v[82:83], v[8:9], v[88:89], v[82:83]
	v_pk_fma_f32 v[84:85], v[6:7], v[86:87], v[84:85]
	v_mov_b32_e32 v86, v98
	v_mov_b32_e32 v87, v100
	v_pk_mul_f32 v[74:75], v[86:87], v[74:75]
	v_mov_b32_e32 v86, v84
	v_mov_b32_e32 v87, v82
	v_mov_b32_e32 v100, v99
	v_pk_mul_f32 v[74:75], v[86:87], v[74:75]
	v_pk_mul_f32 v[76:77], v[100:101], v[76:77]
	v_mov_b32_e32 v82, v85
	v_pk_mul_f32 v[76:77], v[82:83], v[76:77]
	v_and_b32_sdwa v5, v74, v218 dst_sel:DWORD dst_unused:UNUSED_PAD src0_sel:WORD_1 src1_sel:DWORD
	v_and_b32_sdwa v3, v75, v218 dst_sel:DWORD dst_unused:UNUSED_PAD src0_sel:WORD_1 src1_sel:DWORD
	v_add3_u32 v5, v74, v5, s91
	v_and_b32_sdwa v74, v77, v218 dst_sel:DWORD dst_unused:UNUSED_PAD src0_sel:WORD_1 src1_sel:DWORD
	v_add3_u32 v3, v75, v3, s91
	v_and_b32_sdwa v75, v76, v218 dst_sel:DWORD dst_unused:UNUSED_PAD src0_sel:WORD_1 src1_sel:DWORD
	v_add3_u32 v74, v77, v74, s91
	v_add3_u32 v75, v76, v75, s91
	v_and_b32_e32 v74, 0xffff0000, v74
	v_and_b32_e32 v76, 0xffff0000, v75
	v_or_b32_sdwa v75, v74, v3 dst_sel:DWORD dst_unused:UNUSED_PAD src0_sel:DWORD src1_sel:WORD_1
	v_mul_f32_e32 v3, v78, v78
	v_or_b32_sdwa v74, v76, v5 dst_sel:DWORD dst_unused:UNUSED_PAD src0_sel:DWORD src1_sel:WORD_1
	v_fmamk_f32 v3, v3, 0xbdd2d3e2, v220
	v_mul_f32_e32 v5, v79, v79
	v_mul_f32_e32 v3, v78, v3
	v_fmamk_f32 v5, v5, 0xbdd2d3e2, v220
	v_exp_f32_e32 v3, v3
	v_mul_f32_e32 v5, v79, v5
	v_exp_f32_e32 v5, v5
	v_lshl_add_u64 v[76:77], v[158:159], 0, s[46:47]
	v_add_f32_e32 v3, 1.0, v3
	global_store_dwordx2 v[76:77], v[74:75], off
	v_rcp_f32_e32 v74, v3
	v_add_f32_e32 v3, 1.0, v5
	v_mul_f32_e32 v5, v80, v80
	v_fmamk_f32 v5, v5, 0xbdd2d3e2, v220
	v_mul_f32_e32 v75, v81, v81
	v_mul_f32_e32 v5, v80, v5
	v_fmamk_f32 v75, v75, 0xbdd2d3e2, v220
	v_exp_f32_e32 v5, v5
	v_mul_f32_e32 v75, v81, v75
	v_exp_f32_e32 v77, v75
	v_rcp_f32_e32 v76, v3
	v_add_f32_e32 v3, 1.0, v5
	v_rcp_f32_e32 v75, v3
	v_add_f32_e32 v3, 1.0, v77
	v_rcp_f32_e32 v77, v3
	v_mov_b32_e32 v82, v78
	v_mov_b32_e32 v83, v80
	v_mov_b32_e32 v80, v79
	v_pk_mul_f32 v[74:75], v[82:83], v[74:75]
	v_mov_b32_e32 v83, v72
	v_pk_mul_f32 v[76:77], v[80:81], v[76:77]
	v_mov_b32_e32 v72, v71
	v_mov_b32_e32 v82, v70
	v_pk_mul_f32 v[70:71], v[72:73], v[76:77]
	v_pk_mul_f32 v[74:75], v[82:83], v[74:75]
	v_and_b32_sdwa v72, v71, v218 dst_sel:DWORD dst_unused:UNUSED_PAD src0_sel:WORD_1 src1_sel:DWORD
	v_pk_fma_f32 v[62:63], v[26:27], v[62:63], v[30:31]
	v_and_b32_sdwa v3, v75, v218 dst_sel:DWORD dst_unused:UNUSED_PAD src0_sel:WORD_1 src1_sel:DWORD
	v_and_b32_sdwa v73, v70, v218 dst_sel:DWORD dst_unused:UNUSED_PAD src0_sel:WORD_1 src1_sel:DWORD
	v_add3_u32 v71, v71, v72, s91
	v_pk_fma_f32 v[62:63], v[22:23], v[54:55], v[62:63]
	v_and_b32_sdwa v5, v74, v218 dst_sel:DWORD dst_unused:UNUSED_PAD src0_sel:WORD_1 src1_sel:DWORD
	v_add3_u32 v3, v75, v3, s91
	v_add3_u32 v70, v70, v73, s91
	v_and_b32_e32 v71, 0xffff0000, v71
	v_pk_fma_f32 v[62:63], v[18:19], v[46:47], v[62:63]
	v_add3_u32 v5, v74, v5, s91
	v_and_b32_e32 v70, 0xffff0000, v70
	v_or_b32_sdwa v71, v71, v3 dst_sel:DWORD dst_unused:UNUSED_PAD src0_sel:DWORD src1_sel:WORD_1
	v_mul_f32_e32 v3, v62, v62
	v_or_b32_sdwa v70, v70, v5 dst_sel:DWORD dst_unused:UNUSED_PAD src0_sel:DWORD src1_sel:WORD_1
	v_fmamk_f32 v3, v3, 0xbdd2d3e2, v220
	v_mul_f32_e32 v5, v63, v63
	v_mul_f32_e32 v3, v62, v3
	v_fmamk_f32 v5, v5, 0xbdd2d3e2, v220
	v_exp_f32_e32 v3, v3
	v_mul_f32_e32 v5, v63, v5
	v_pk_fma_f32 v[64:65], v[28:29], v[64:65], v[32:33]
	v_pk_fma_f32 v[28:29], v[28:29], v[56:57], v[32:33]
	v_exp_f32_e32 v5, v5
	v_pk_fma_f32 v[64:65], v[24:25], v[56:57], v[64:65]
	v_pk_fma_f32 v[24:25], v[24:25], v[48:49], v[28:29]
	v_pk_fma_f32 v[64:65], v[20:21], v[48:49], v[64:65]
	v_pk_fma_f32 v[20:21], v[20:21], v[52:53], v[24:25]
	v_pk_fma_f32 v[24:25], v[10:11], v[66:67], v[34:35]
	v_pk_fma_f32 v[10:11], v[10:11], v[42:43], v[34:35]
	v_pk_fma_f32 v[24:25], v[14:15], v[42:43], v[24:25]
	v_pk_fma_f32 v[10:11], v[14:15], v[58:59], v[10:11]
	v_add_f32_e32 v3, 1.0, v3
	v_pk_fma_f32 v[26:27], v[26:27], v[54:55], v[30:31]
	v_pk_fma_f32 v[24:25], v[6:7], v[58:59], v[24:25]
	v_pk_fma_f32 v[6:7], v[6:7], v[38:39], v[10:11]
	v_rcp_f32_e32 v10, v3
	v_add_f32_e32 v3, 1.0, v5
	v_mul_f32_e32 v5, v64, v64
	v_pk_fma_f32 v[22:23], v[22:23], v[46:47], v[26:27]
	v_fmamk_f32 v5, v5, 0xbdd2d3e2, v220
	v_mul_f32_e32 v11, v65, v65
	v_pk_fma_f32 v[18:19], v[18:19], v[50:51], v[22:23]
	v_pk_fma_f32 v[22:23], v[12:13], v[68:69], v[36:37]
	v_pk_fma_f32 v[12:13], v[12:13], v[44:45], v[36:37]
	v_mul_f32_e32 v5, v64, v5
	v_fmamk_f32 v11, v11, 0xbdd2d3e2, v220
	v_pk_fma_f32 v[22:23], v[16:17], v[44:45], v[22:23]
	v_pk_fma_f32 v[12:13], v[16:17], v[60:61], v[12:13]
	v_exp_f32_e32 v5, v5
	v_mul_f32_e32 v11, v65, v11
	v_pk_fma_f32 v[22:23], v[8:9], v[60:61], v[22:23]
	v_pk_fma_f32 v[8:9], v[8:9], v[40:41], v[12:13]
	v_exp_f32_e32 v13, v11
	v_rcp_f32_e32 v12, v3
	v_add_f32_e32 v3, 1.0, v5
	v_rcp_f32_e32 v11, v3
	v_add_f32_e32 v3, 1.0, v13
	v_rcp_f32_e32 v13, v3
	v_mov_b32_e32 v14, v62
	v_mov_b32_e32 v15, v64
	v_pk_mul_f32 v[10:11], v[14:15], v[10:11]
	v_mov_b32_e32 v14, v24
	v_mov_b32_e32 v15, v22
	v_mov_b32_e32 v64, v63
	v_pk_mul_f32 v[10:11], v[14:15], v[10:11]
	v_pk_mul_f32 v[12:13], v[64:65], v[12:13]
	v_mov_b32_e32 v22, v25
	v_pk_mul_f32 v[12:13], v[22:23], v[12:13]
	v_and_b32_sdwa v5, v10, v218 dst_sel:DWORD dst_unused:UNUSED_PAD src0_sel:WORD_1 src1_sel:DWORD
	v_and_b32_sdwa v3, v11, v218 dst_sel:DWORD dst_unused:UNUSED_PAD src0_sel:WORD_1 src1_sel:DWORD
	v_add3_u32 v5, v10, v5, s91
	v_and_b32_sdwa v10, v13, v218 dst_sel:DWORD dst_unused:UNUSED_PAD src0_sel:WORD_1 src1_sel:DWORD
	v_add3_u32 v3, v11, v3, s91
	v_and_b32_sdwa v11, v12, v218 dst_sel:DWORD dst_unused:UNUSED_PAD src0_sel:WORD_1 src1_sel:DWORD
	v_add3_u32 v10, v13, v10, s91
	v_add3_u32 v11, v12, v11, s91
	v_and_b32_e32 v10, 0xffff0000, v10
	v_and_b32_e32 v12, 0xffff0000, v11
	v_or_b32_sdwa v11, v10, v3 dst_sel:DWORD dst_unused:UNUSED_PAD src0_sel:DWORD src1_sel:WORD_1
	v_mul_f32_e32 v3, v18, v18
	v_or_b32_sdwa v10, v12, v5 dst_sel:DWORD dst_unused:UNUSED_PAD src0_sel:DWORD src1_sel:WORD_1
	v_fmamk_f32 v3, v3, 0xbdd2d3e2, v220
	v_mul_f32_e32 v5, v19, v19
	v_mul_f32_e32 v3, v18, v3
	v_fmamk_f32 v5, v5, 0xbdd2d3e2, v220
	v_exp_f32_e32 v3, v3
	v_mul_f32_e32 v5, v19, v5
	v_exp_f32_e32 v5, v5
	v_lshl_add_u64 v[12:13], v[158:159], 0, s[50:51]
	v_add_f32_e32 v3, 1.0, v3
	global_store_dwordx2 v[12:13], v[10:11], off
	v_rcp_f32_e32 v10, v3
	v_add_f32_e32 v3, 1.0, v5
	v_mul_f32_e32 v5, v20, v20
	v_fmamk_f32 v5, v5, 0xbdd2d3e2, v220
	v_mul_f32_e32 v11, v21, v21
	v_mul_f32_e32 v5, v20, v5
	v_fmamk_f32 v11, v11, 0xbdd2d3e2, v220
	v_exp_f32_e32 v5, v5
	v_mul_f32_e32 v11, v21, v11
	v_exp_f32_e32 v13, v11
	v_rcp_f32_e32 v12, v3
	v_add_f32_e32 v3, 1.0, v5
	v_rcp_f32_e32 v11, v3
	v_add_f32_e32 v3, 1.0, v13
	v_rcp_f32_e32 v13, v3
	v_mov_b32_e32 v14, v18
	v_mov_b32_e32 v15, v20
	v_mov_b32_e32 v20, v19
	v_pk_mul_f32 v[10:11], v[14:15], v[10:11]
	v_mov_b32_e32 v15, v8
	v_pk_mul_f32 v[12:13], v[20:21], v[12:13]
	v_mov_b32_e32 v8, v7
	v_mov_b32_e32 v14, v6
	v_pk_mul_f32 v[6:7], v[8:9], v[12:13]
	v_pk_mul_f32 v[10:11], v[14:15], v[10:11]
	v_and_b32_sdwa v8, v7, v218 dst_sel:DWORD dst_unused:UNUSED_PAD src0_sel:WORD_1 src1_sel:DWORD
	v_and_b32_sdwa v9, v6, v218 dst_sel:DWORD dst_unused:UNUSED_PAD src0_sel:WORD_1 src1_sel:DWORD
	v_and_b32_sdwa v3, v11, v218 dst_sel:DWORD dst_unused:UNUSED_PAD src0_sel:WORD_1 src1_sel:DWORD
	v_and_b32_sdwa v5, v10, v218 dst_sel:DWORD dst_unused:UNUSED_PAD src0_sel:WORD_1 src1_sel:DWORD
	v_add3_u32 v7, v7, v8, s91
	v_add3_u32 v6, v6, v9, s91
	v_add_u32_e32 v0, 0x200, v0
	v_add3_u32 v5, v10, v5, s91
	v_add3_u32 v3, v11, v3, s91
	v_and_b32_e32 v7, 0xffff0000, v7
	v_and_b32_e32 v6, 0xffff0000, v6
	v_cmp_lt_i32_e32 vcc, s66, v0
	v_lshl_add_u64 v[136:137], v[158:159], 0, s[40:41]
	v_lshl_add_u64 v[104:105], v[158:159], 0, s[44:45]
	v_lshl_add_u64 v[72:73], v[158:159], 0, s[48:49]
	v_or_b32_sdwa v7, v7, v3 dst_sel:DWORD dst_unused:UNUSED_PAD src0_sel:DWORD src1_sel:WORD_1
	v_or_b32_sdwa v6, v6, v5 dst_sel:DWORD dst_unused:UNUSED_PAD src0_sel:DWORD src1_sel:WORD_1
	v_lshl_add_u64 v[8:9], v[158:159], 0, s[52:53]
	s_or_b64 s[54:55], vcc, s[54:55]
	v_add_u32_e32 v2, 0x800, v2
	global_store_dwordx2 v[136:137], v[134:135], off
	global_store_dwordx2 v[104:105], v[102:103], off
	global_store_dwordx2 v[72:73], v[70:71], off
	global_store_dwordx2 v[8:9], v[6:7], off
	s_andn2_b64 exec, exec, s[54:55]
	s_cbranch_execz .LBB0_294
